# P2 GEMM first K-iteration peeled (first MFMA per accumulator takes C=0, the 128 per-unit zeroing v_movs removed), 4-byte pad keeps downstream code phase
# speedup vs baseline: 1.0341x; 1.0058x over previous
.LBB0_281:
	s_ashr_i32 s57, s56, 31
	s_lshl_b64 s[4:5], s[56:57], 19
	s_add_u32 s62, s40, s4
	s_addc_u32 s63, s41, s5
	s_and_b64 s[4:5], s[84:85], exec
	s_cselect_b32 s4, s63, s1
	s_cselect_b32 s5, s62, s0
	s_ashr_i32 s59, s58, 31
	s_lshl_b64 s[64:65], s[58:59], 19
	s_add_u32 s64, s42, s64
	s_addc_u32 s65, s43, s65
	s_and_b64 s[84:85], s[84:85], exec
	s_cselect_b32 s57, s65, s83
	s_cselect_b32 s59, s64, s82
	s_add_u32 s0, s0, 0x40080
	s_addc_u32 s1, s1, 0
	s_add_u32 s67, s82, 0x100
	s_addc_u32 s81, s83, 0
	s_mov_b32 s97, -2
	s_nop 0
	ds_read_b128 v[144:147], v164
	ds_read_b128 v[148:151], v164 offset:1024
	ds_read_b128 v[152:155], v164 offset:2048
	ds_read_b128 v[156:159], v164 offset:3072
	s_add_u32 s33, s0, 0xfffc0080
	s_addc_u32 s82, s1, -1
	s_cmp_eq_u32 s97, 12
	s_cselect_b32 s85, s4, s82
	s_cselect_b32 s84, s5, s33
	s_cselect_b32 s83, s57, s81
	s_cselect_b32 s82, s59, s67
	v_lshl_add_u64 v[160:161], s[0:1], 0, v[140:141]
	s_add_i32 m0, s13, 0xc000
	ds_read_b128 v[172:175], v165
	ds_read_b128 v[176:179], v165 offset:1024
	ds_read_b128 v[180:183], v165 offset:2048
	ds_read_b128 v[184:187], v165 offset:3072
	ds_read_b128 v[188:191], v165 offset:4096
	ds_read_b128 v[192:195], v165 offset:5120
	ds_read_b128 v[196:199], v165 offset:6144
	ds_read_b128 v[200:203], v165 offset:7168
	global_load_lds_dwordx4 v[160:161], off
	v_lshl_add_u64 v[160:161], s[0:1], 0, v[142:143]
	s_add_i32 m0, s13, 0xe000
	s_nop 0
	global_load_lds_dwordx4 v[160:161], off
	s_waitcnt lgkmcnt(8)
	s_barrier
	s_waitcnt lgkmcnt(0)
	s_waitcnt lgkmcnt(0)
	v_mfma_f32_16x16x32_bf16 v[124:127], v[144:147], v[172:175], 0
	v_mfma_f32_16x16x32_bf16 v[92:95], v[152:155], v[172:175], 0
	v_mfma_f32_16x16x32_bf16 v[120:123], v[144:147], v[180:183], 0
	v_mfma_f32_16x16x32_bf16 v[88:91], v[152:155], v[180:183], 0
	v_mfma_f32_16x16x32_bf16 v[116:119], v[144:147], v[188:191], 0
	v_mfma_f32_16x16x32_bf16 v[84:87], v[152:155], v[188:191], 0
	v_mfma_f32_16x16x32_bf16 v[112:115], v[144:147], v[196:199], 0
	v_mfma_f32_16x16x32_bf16 v[80:83], v[152:155], v[196:199], 0
	v_mfma_f32_16x16x32_bf16 v[124:127], v[148:151], v[176:179], v[124:127]
	v_mfma_f32_16x16x32_bf16 v[92:95], v[156:159], v[176:179], v[92:95]
	v_mfma_f32_16x16x32_bf16 v[120:123], v[148:151], v[184:187], v[120:123]
	v_mfma_f32_16x16x32_bf16 v[88:91], v[156:159], v[184:187], v[88:91]
	v_mfma_f32_16x16x32_bf16 v[116:119], v[148:151], v[192:195], v[116:119]
	v_mfma_f32_16x16x32_bf16 v[84:87], v[156:159], v[192:195], v[84:87]
	v_mfma_f32_16x16x32_bf16 v[112:115], v[148:151], v[200:203], v[112:115]
	v_mfma_f32_16x16x32_bf16 v[80:83], v[156:159], v[200:203], v[80:83]
	s_barrier
	s_add_i32 s33, s89, s11
	v_lshl_add_u64 v[160:161], s[82:83], 0, v[130:131]
	s_mov_b32 m0, s33
	ds_read_b128 v[204:207], v166
	ds_read_b128 v[208:211], v166 offset:1024
	ds_read_b128 v[212:215], v166 offset:2048
	ds_read_b128 v[218:221], v166 offset:3072
	global_load_lds_dwordx4 v[160:161], off
	v_lshl_add_u64 v[222:223], s[82:83], 0, v[134:135]
	s_add_i32 m0, s33, 0x2000
	s_nop 0
	global_load_lds_dwordx4 v[222:223], off
	s_barrier
	s_waitcnt lgkmcnt(0)
	s_waitcnt lgkmcnt(0)
	v_mfma_f32_16x16x32_bf16 v[60:63], v[204:207], v[172:175], 0
	v_mfma_f32_16x16x32_bf16 v[28:31], v[212:215], v[172:175], 0
	v_mfma_f32_16x16x32_bf16 v[56:59], v[204:207], v[180:183], 0
	v_mfma_f32_16x16x32_bf16 v[24:27], v[212:215], v[180:183], 0
	v_mfma_f32_16x16x32_bf16 v[52:55], v[204:207], v[188:191], 0
	v_mfma_f32_16x16x32_bf16 v[20:23], v[212:215], v[188:191], 0
	v_mfma_f32_16x16x32_bf16 v[48:51], v[204:207], v[196:199], 0
	v_mfma_f32_16x16x32_bf16 v[16:19], v[212:215], v[196:199], 0
	v_mfma_f32_16x16x32_bf16 v[60:63], v[208:211], v[176:179], v[60:63]
	v_mfma_f32_16x16x32_bf16 v[28:31], v[218:221], v[176:179], v[28:31]
	v_mfma_f32_16x16x32_bf16 v[56:59], v[208:211], v[184:187], v[56:59]
	v_mfma_f32_16x16x32_bf16 v[24:27], v[218:221], v[184:187], v[24:27]
	v_mfma_f32_16x16x32_bf16 v[52:55], v[208:211], v[192:195], v[52:55]
	v_mfma_f32_16x16x32_bf16 v[20:23], v[218:221], v[192:195], v[20:23]
	v_mfma_f32_16x16x32_bf16 v[48:51], v[208:211], v[200:203], v[48:51]
	v_mfma_f32_16x16x32_bf16 v[16:19], v[218:221], v[200:203], v[16:19]
	s_mov_b32 m0, s13
	v_lshl_add_u64 v[224:225], s[84:85], 0, v[128:129]
	s_barrier
	ds_read_b128 v[172:175], v165 offset:16384
	ds_read_b128 v[176:179], v165 offset:17408
	ds_read_b128 v[180:183], v165 offset:18432
	ds_read_b128 v[184:187], v165 offset:19456
	ds_read_b128 v[188:191], v165 offset:20480
	ds_read_b128 v[192:195], v165 offset:21504
	ds_read_b128 v[196:199], v165 offset:22528
	ds_read_b128 v[200:203], v165 offset:23552
	global_load_lds_dwordx4 v[224:225], off
	v_lshl_add_u64 v[226:227], s[84:85], 0, v[132:133]
	s_mov_b32 m0, s15
	s_nop 0
	global_load_lds_dwordx4 v[226:227], off
	s_barrier
	s_waitcnt lgkmcnt(0)
	s_waitcnt lgkmcnt(0)
	v_mfma_f32_16x16x32_bf16 v[108:111], v[144:147], v[172:175], 0
	v_mfma_f32_16x16x32_bf16 v[76:79], v[152:155], v[172:175], 0
	v_mfma_f32_16x16x32_bf16 v[104:107], v[144:147], v[180:183], 0
	v_mfma_f32_16x16x32_bf16 v[72:75], v[152:155], v[180:183], 0
	v_mfma_f32_16x16x32_bf16 v[100:103], v[144:147], v[188:191], 0
	v_mfma_f32_16x16x32_bf16 v[68:71], v[152:155], v[188:191], 0
	v_mfma_f32_16x16x32_bf16 v[96:99], v[144:147], v[196:199], 0
	v_mfma_f32_16x16x32_bf16 v[64:67], v[152:155], v[196:199], 0
	v_mfma_f32_16x16x32_bf16 v[108:111], v[148:151], v[176:179], v[108:111]
	v_mfma_f32_16x16x32_bf16 v[76:79], v[156:159], v[176:179], v[76:79]
	v_mfma_f32_16x16x32_bf16 v[104:107], v[148:151], v[184:187], v[104:107]
	v_mfma_f32_16x16x32_bf16 v[72:75], v[156:159], v[184:187], v[72:75]
	v_mfma_f32_16x16x32_bf16 v[100:103], v[148:151], v[192:195], v[100:103]
	v_mfma_f32_16x16x32_bf16 v[68:71], v[156:159], v[192:195], v[68:71]
	v_mfma_f32_16x16x32_bf16 v[96:99], v[148:151], v[200:203], v[96:99]
	v_mfma_f32_16x16x32_bf16 v[64:67], v[156:159], v[200:203], v[64:67]
	s_barrier
	s_add_u32 vcc_lo, s82, 0x40000
	s_addc_u32 vcc_hi, s83, 0
	s_add_i32 s33, s91, s11
	v_lshl_add_u64 v[144:145], vcc, 0, v[130:131]
	s_mov_b32 m0, s33
	s_nop 0
	global_load_lds_dwordx4 v[144:145], off
	v_lshl_add_u64 v[144:145], vcc, 0, v[134:135]
	s_add_i32 m0, s33, 0x2000
	s_nop 0
	global_load_lds_dwordx4 v[144:145], off
	s_waitcnt vmcnt(6)
	s_barrier
	v_mfma_f32_16x16x32_bf16 v[44:47], v[204:207], v[172:175], 0
	v_mfma_f32_16x16x32_bf16 v[12:15], v[212:215], v[172:175], 0
	v_mfma_f32_16x16x32_bf16 v[40:43], v[204:207], v[180:183], 0
	v_mfma_f32_16x16x32_bf16 v[8:11], v[212:215], v[180:183], 0
	v_mfma_f32_16x16x32_bf16 v[36:39], v[204:207], v[188:191], 0
	v_mfma_f32_16x16x32_bf16 v[4:7], v[212:215], v[188:191], 0
	v_mfma_f32_16x16x32_bf16 v[32:35], v[204:207], v[196:199], 0
	v_mfma_f32_16x16x32_bf16 v[0:3], v[212:215], v[196:199], 0
	v_mfma_f32_16x16x32_bf16 v[44:47], v[208:211], v[176:179], v[44:47]
	v_mfma_f32_16x16x32_bf16 v[12:15], v[218:221], v[176:179], v[12:15]
	v_mfma_f32_16x16x32_bf16 v[40:43], v[208:211], v[184:187], v[40:43]
	v_mfma_f32_16x16x32_bf16 v[8:11], v[218:221], v[184:187], v[8:11]
	v_mfma_f32_16x16x32_bf16 v[36:39], v[208:211], v[192:195], v[36:39]
	v_mfma_f32_16x16x32_bf16 v[4:7], v[218:221], v[192:195], v[4:7]
	v_mfma_f32_16x16x32_bf16 v[32:35], v[208:211], v[200:203], v[32:35]
	v_mfma_f32_16x16x32_bf16 v[0:3], v[218:221], v[200:203], v[0:3]
	s_add_i32 s33, 0, 0x18000
	v_add_u32_e32 v136, s33, v162
	s_barrier
	ds_read_b128 v[144:147], v136
	ds_read_b128 v[148:151], v136 offset:1024
	ds_read_b128 v[152:155], v136 offset:2048
	ds_read_b128 v[156:159], v136 offset:3072
	s_add_u32 s84, s84, 0x40000
	s_addc_u32 s85, s85, 0
	s_mov_b32 m0, s19
	v_lshl_add_u64 v[204:205], s[84:85], 0, v[128:129]
	ds_read_b128 v[172:175], v165 offset:32768
	ds_read_b128 v[176:179], v165 offset:33792
	ds_read_b128 v[180:183], v165 offset:34816
	ds_read_b128 v[184:187], v165 offset:35840
	ds_read_b128 v[188:191], v165 offset:36864
	ds_read_b128 v[192:195], v165 offset:37888
	ds_read_b128 v[196:199], v165 offset:38912
	ds_read_b128 v[200:203], v165 offset:39936
	global_load_lds_dwordx4 v[204:205], off
	v_lshl_add_u64 v[204:205], s[84:85], 0, v[132:133]
	s_mov_b32 m0, s37
	s_nop 0
	global_load_lds_dwordx4 v[204:205], off
	s_waitcnt lgkmcnt(8)
	s_barrier
	s_waitcnt lgkmcnt(0)
	s_waitcnt lgkmcnt(0)
	v_mfma_f32_16x16x32_bf16 v[124:127], v[144:147], v[172:175], v[124:127]
	v_mfma_f32_16x16x32_bf16 v[92:95], v[152:155], v[172:175], v[92:95]
	v_mfma_f32_16x16x32_bf16 v[120:123], v[144:147], v[180:183], v[120:123]
	v_mfma_f32_16x16x32_bf16 v[88:91], v[152:155], v[180:183], v[88:91]
	v_mfma_f32_16x16x32_bf16 v[116:119], v[144:147], v[188:191], v[116:119]
	v_mfma_f32_16x16x32_bf16 v[84:87], v[152:155], v[188:191], v[84:87]
	v_mfma_f32_16x16x32_bf16 v[112:115], v[144:147], v[196:199], v[112:115]
	v_mfma_f32_16x16x32_bf16 v[80:83], v[152:155], v[196:199], v[80:83]
	v_mfma_f32_16x16x32_bf16 v[124:127], v[148:151], v[176:179], v[124:127]
	v_mfma_f32_16x16x32_bf16 v[92:95], v[156:159], v[176:179], v[92:95]
	v_mfma_f32_16x16x32_bf16 v[120:123], v[148:151], v[184:187], v[120:123]
	v_mfma_f32_16x16x32_bf16 v[88:91], v[156:159], v[184:187], v[88:91]
	v_mfma_f32_16x16x32_bf16 v[116:119], v[148:151], v[192:195], v[116:119]
	v_mfma_f32_16x16x32_bf16 v[84:87], v[156:159], v[192:195], v[84:87]
	v_mfma_f32_16x16x32_bf16 v[112:115], v[148:151], v[200:203], v[112:115]
	v_mfma_f32_16x16x32_bf16 v[80:83], v[156:159], v[200:203], v[80:83]
	s_barrier
	s_add_i32 s84, 0, 0x1c000
	s_add_i32 s33, s33, s11
	v_add_u32_e32 v136, s84, v162
	v_lshl_add_u64 v[160:161], v[160:161], 0, s[6:7]
	s_mov_b32 m0, s33
	ds_read_b128 v[204:207], v136
	ds_read_b128 v[208:211], v136 offset:1024
	ds_read_b128 v[212:215], v136 offset:2048
	ds_read_b128 v[218:221], v136 offset:3072
	global_load_lds_dwordx4 v[160:161], off
	v_lshl_add_u64 v[160:161], v[222:223], 0, s[6:7]
	s_add_i32 m0, s33, 0x2000
	s_nop 0
	global_load_lds_dwordx4 v[160:161], off
	s_barrier
	s_waitcnt lgkmcnt(0)
	s_waitcnt lgkmcnt(0)
	v_mfma_f32_16x16x32_bf16 v[60:63], v[204:207], v[172:175], v[60:63]
	v_mfma_f32_16x16x32_bf16 v[28:31], v[212:215], v[172:175], v[28:31]
	v_mfma_f32_16x16x32_bf16 v[56:59], v[204:207], v[180:183], v[56:59]
	v_mfma_f32_16x16x32_bf16 v[24:27], v[212:215], v[180:183], v[24:27]
	v_mfma_f32_16x16x32_bf16 v[52:55], v[204:207], v[188:191], v[52:55]
	v_mfma_f32_16x16x32_bf16 v[20:23], v[212:215], v[188:191], v[20:23]
	v_mfma_f32_16x16x32_bf16 v[48:51], v[204:207], v[196:199], v[48:51]
	v_mfma_f32_16x16x32_bf16 v[16:19], v[212:215], v[196:199], v[16:19]
	v_mfma_f32_16x16x32_bf16 v[60:63], v[208:211], v[176:179], v[60:63]
	v_mfma_f32_16x16x32_bf16 v[28:31], v[218:221], v[176:179], v[28:31]
	v_mfma_f32_16x16x32_bf16 v[56:59], v[208:211], v[184:187], v[56:59]
	v_mfma_f32_16x16x32_bf16 v[24:27], v[218:221], v[184:187], v[24:27]
	v_mfma_f32_16x16x32_bf16 v[52:55], v[208:211], v[192:195], v[52:55]
	v_mfma_f32_16x16x32_bf16 v[20:23], v[218:221], v[192:195], v[20:23]
	v_mfma_f32_16x16x32_bf16 v[48:51], v[208:211], v[200:203], v[48:51]
	v_mfma_f32_16x16x32_bf16 v[16:19], v[218:221], v[200:203], v[16:19]
	s_mov_b32 m0, s86
	v_lshl_add_u64 v[160:161], v[224:225], 0, s[6:7]
	s_barrier
	ds_read_b128 v[172:175], v165 offset:49152
	ds_read_b128 v[176:179], v165 offset:50176
	ds_read_b128 v[180:183], v165 offset:51200
	ds_read_b128 v[184:187], v165 offset:52224
	ds_read_b128 v[188:191], v165 offset:53248
	ds_read_b128 v[192:195], v165 offset:54272
	ds_read_b128 v[196:199], v165 offset:55296
	ds_read_b128 v[200:203], v165 offset:56320
	global_load_lds_dwordx4 v[160:161], off
	v_lshl_add_u64 v[160:161], v[226:227], 0, s[6:7]
	s_mov_b32 m0, s87
	s_nop 0
	global_load_lds_dwordx4 v[160:161], off
	s_barrier
	s_waitcnt lgkmcnt(0)
	s_waitcnt lgkmcnt(0)
	v_mfma_f32_16x16x32_bf16 v[108:111], v[144:147], v[172:175], v[108:111]
	v_mfma_f32_16x16x32_bf16 v[76:79], v[152:155], v[172:175], v[76:79]
	v_mfma_f32_16x16x32_bf16 v[104:107], v[144:147], v[180:183], v[104:107]
	v_mfma_f32_16x16x32_bf16 v[72:75], v[152:155], v[180:183], v[72:75]
	v_mfma_f32_16x16x32_bf16 v[100:103], v[144:147], v[188:191], v[100:103]
	v_mfma_f32_16x16x32_bf16 v[68:71], v[152:155], v[188:191], v[68:71]
	v_mfma_f32_16x16x32_bf16 v[96:99], v[144:147], v[196:199], v[96:99]
	v_mfma_f32_16x16x32_bf16 v[64:67], v[152:155], v[196:199], v[64:67]
	v_mfma_f32_16x16x32_bf16 v[108:111], v[148:151], v[176:179], v[108:111]
	v_mfma_f32_16x16x32_bf16 v[76:79], v[156:159], v[176:179], v[76:79]
	v_mfma_f32_16x16x32_bf16 v[104:107], v[148:151], v[184:187], v[104:107]
	v_mfma_f32_16x16x32_bf16 v[72:75], v[156:159], v[184:187], v[72:75]
	v_mfma_f32_16x16x32_bf16 v[100:103], v[148:151], v[192:195], v[100:103]
	v_mfma_f32_16x16x32_bf16 v[68:71], v[156:159], v[192:195], v[68:71]
	v_mfma_f32_16x16x32_bf16 v[96:99], v[148:151], v[200:203], v[96:99]
	v_mfma_f32_16x16x32_bf16 v[64:67], v[156:159], v[200:203], v[64:67]
	s_barrier
	s_add_u32 s82, s82, 0x40080
	s_addc_u32 s83, s83, 0
	s_add_i32 s33, s84, s11
	v_lshl_add_u64 v[144:145], s[82:83], 0, v[130:131]
	s_mov_b32 m0, s33
	s_nop 0
	global_load_lds_dwordx4 v[144:145], off
	v_lshl_add_u64 v[144:145], s[82:83], 0, v[134:135]
	s_add_i32 m0, s33, 0x2000
	s_nop 0
	global_load_lds_dwordx4 v[144:145], off
	s_waitcnt vmcnt(6)
	s_barrier
	v_mfma_f32_16x16x32_bf16 v[44:47], v[204:207], v[172:175], v[44:47]
	v_mfma_f32_16x16x32_bf16 v[12:15], v[212:215], v[172:175], v[12:15]
	v_mfma_f32_16x16x32_bf16 v[40:43], v[204:207], v[180:183], v[40:43]
	v_mfma_f32_16x16x32_bf16 v[8:11], v[212:215], v[180:183], v[8:11]
	v_mfma_f32_16x16x32_bf16 v[36:39], v[204:207], v[188:191], v[36:39]
	v_mfma_f32_16x16x32_bf16 v[4:7], v[212:215], v[188:191], v[4:7]
	v_mfma_f32_16x16x32_bf16 v[32:35], v[204:207], v[196:199], v[32:35]
	v_mfma_f32_16x16x32_bf16 v[0:3], v[212:215], v[196:199], v[0:3]
	v_mfma_f32_16x16x32_bf16 v[44:47], v[208:211], v[176:179], v[44:47]
	v_mfma_f32_16x16x32_bf16 v[12:15], v[218:221], v[176:179], v[12:15]
	v_mfma_f32_16x16x32_bf16 v[40:43], v[208:211], v[184:187], v[40:43]
	v_mfma_f32_16x16x32_bf16 v[8:11], v[218:221], v[184:187], v[8:11]
	v_mfma_f32_16x16x32_bf16 v[36:39], v[208:211], v[192:195], v[36:39]
	v_mfma_f32_16x16x32_bf16 v[4:7], v[218:221], v[192:195], v[4:7]
	v_mfma_f32_16x16x32_bf16 v[32:35], v[208:211], v[200:203], v[32:35]
	v_mfma_f32_16x16x32_bf16 v[0:3], v[218:221], v[200:203], v[0:3]
	s_add_i32 s97, s97, 2
	s_add_u32 s0, s0, 0x100
	s_addc_u32 s1, s1, 0
	s_add_u32 s67, s67, 0x100
	s_addc_u32 s81, s81, 0
	s_cmp_gt_u32 s97, 13
	s_barrier
